# attention K/V prefetch addresses: SGPR running bases plus one 64-bit add per load, no vcc chains or VALU pointer increments
# speedup vs baseline: 1.0020x; 1.0020x over previous
.LBB0_1726:
	s_waitcnt lgkmcnt(8)
	v_add_f32_e32 v11, v11, v76
	v_fmamk_f32 v11, v11, 0x3c000000, v158
	v_mul_f32_e32 v76, 0x4b800000, v11
	v_cmp_gt_f32_e32 vcc, s92, v11
	v_lshlrev_b64 v[148:149], 11, v[12:13]
	s_waitcnt lgkmcnt(6)
	v_add_f32_e32 v13, v79, v80
	v_cndmask_b32_e32 v11, v11, v76, vcc
	v_rsq_f32_e32 v11, v11
	s_waitcnt lgkmcnt(4)
	v_add_f32_e32 v76, v83, v84
	s_waitcnt lgkmcnt(2)
	v_add_f32_e32 v79, v87, v88
	s_waitcnt lgkmcnt(1)
	v_add_f32_e32 v80, v89, v90
	v_mul_f32_e32 v12, 0x45800000, v11
	v_cndmask_b32_e32 v11, v11, v12, vcc
	v_mul_f32_e32 v12, 0x3e0293ee, v11
	v_add_f32_e32 v11, v75, v78
	v_cmp_lg_f32_e32 vcc, s93, v11
	v_add_f32_e32 v75, v81, v82
	v_add_f32_e32 v78, v85, v86
	v_cndmask_b32_e32 v82, v159, v11, vcc
	v_cmp_gt_f32_e32 vcc, v13, v82
	s_waitcnt lgkmcnt(0)
	v_add_f32_e32 v81, v91, v93
	v_and_b32_e32 v77, 31, v4
	v_cndmask_b32_e32 v82, v82, v13, vcc
	v_cndmask_b32_e64 v83, 0, 1, vcc
	v_cmp_gt_f32_e32 vcc, v75, v82
	s_lshl_b32 s79, s81, 2
	v_and_b32_e32 v177, 0xf0, v6
	v_cndmask_b32_e32 v82, v82, v75, vcc
	v_cmp_gt_f32_e64 s[0:1], v76, v82
	v_mul_lo_u32 v176, v10, s97
	v_and_b32_e32 v178, 0x70, v6
	v_cndmask_b32_e64 v82, v82, v76, s[0:1]
	v_cmp_gt_f32_e64 s[4:5], v78, v82
	v_lshlrev_b32_e32 v147, 2, v5
	v_lshl_add_u64 v[152:153], s[88:89], 0, v[6:7]
	v_cndmask_b32_e64 v82, v82, v78, s[4:5]
	v_cmp_gt_f32_e64 s[8:9], v79, v82
	v_mov_b32_e32 v5, v145
	v_mov_b32_e32 v7, v145
	v_cndmask_b32_e64 v82, v82, v79, s[8:9]
	v_cmp_gt_f32_e64 s[10:11], v80, v82
	v_mov_b32_e32 v10, v145
	v_and_b32_e32 v172, 0xffffffe0, v74
	v_cndmask_b32_e64 v82, v82, v80, s[10:11]
	v_cmp_gt_f32_e64 s[14:15], v81, v82
	s_mov_b32 s84, 0
	s_add_u32 s98, s12, s6
	s_addc_u32 s99, s13, 0
	s_add_u32 s100, s12, s7
	s_addc_u32 s101, s13, 0
	s_add_u32 s44, s12, s59
	s_addc_u32 s45, s13, 0
	s_add_u32 s46, s12, 0x31e80000
	s_addc_u32 s47, s13, 0
	v_or_b32_e32 v175, 31, v74
	v_cndmask_b32_e64 v82, v82, v81, s[14:15]
	v_cmp_gt_f32_e64 s[16:17], v92, v82
	s_and_b64 s[16:17], s[66:67], s[16:17]
	v_mul_u32_u24_e32 v174, 0x110, v77
	v_cndmask_b32_e64 v82, v82, v92, s[16:17]
	v_cmp_gt_f32_e64 s[18:19], v95, v82
	s_and_b64 s[18:19], s[68:69], s[18:19]
	v_mul_u32_u24_e32 v171, 0x90, v77
	v_cndmask_b32_e64 v82, v82, v95, s[18:19]
	v_cmp_gt_f32_e64 s[20:21], v94, v82
	s_and_b64 s[20:21], s[70:71], s[20:21]
	v_mov_b32_e32 v154, 0xf149f2ca
	v_cndmask_b32_e64 v82, v82, v94, s[20:21]
	v_cmp_gt_f32_e64 s[22:23], v113, v82
	s_and_b64 s[22:23], s[72:73], s[22:23]
	v_mov_b32_e32 v170, 0
	v_cndmask_b32_e64 v82, v82, v113, s[22:23]
	v_cmp_gt_f32_e64 s[24:25], v112, v82
	s_and_b64 s[24:25], s[74:75], s[24:25]
	s_nop 0
	v_cndmask_b32_e64 v82, v82, v112, s[24:25]
	v_cmp_gt_f32_e64 s[26:27], v115, v82
	s_and_b64 s[26:27], s[76:77], s[26:27]
	s_nop 0
	v_cndmask_b32_e64 v82, v82, v115, s[26:27]
	v_cmp_gt_f32_e64 s[28:29], v114, v82
	v_lshlrev_b32_e64 v82, v83, 1
	v_cndmask_b32_e64 v82, v82, 4, vcc
	v_cndmask_b32_e64 v82, v82, 8, s[0:1]
	v_cndmask_b32_e64 v82, v82, 16, s[4:5]
	v_cndmask_b32_e64 v82, v82, 32, s[8:9]
	v_cndmask_b32_e64 v82, v82, 64, s[10:11]
	v_cndmask_b32_e64 v82, v82, v160, s[14:15]
	v_cndmask_b32_e64 v82, v82, v161, s[16:17]
	v_cndmask_b32_e64 v82, v82, v162, s[18:19]
	v_cndmask_b32_e64 v82, v82, v163, s[20:21]
	v_cndmask_b32_e64 v82, v82, v164, s[22:23]
	v_cndmask_b32_e64 v82, v82, v165, s[24:25]
	v_cndmask_b32_e64 v82, v82, v166, s[26:27]
	s_and_b64 vcc, s[30:31], s[28:29]
	v_cndmask_b32_e32 v82, v82, v167, vcc
	v_and_b32_e32 v83, 1, v82
	v_cmp_eq_u32_e64 s[0:1], 1, v83
	v_cmp_nlg_f32_e32 vcc, s93, v11
	s_or_b64 s[0:1], s[0:1], vcc
	v_cndmask_b32_e64 v83, v11, v159, s[0:1]
	v_and_b32_e32 v84, 2, v82
	v_cmp_eq_u32_e64 s[0:1], 0, v84
	v_cmp_gt_f32_e64 s[4:5], v13, v83
	s_and_b64 s[0:1], s[0:1], s[4:5]
	v_cndmask_b32_e64 v83, v83, v13, s[0:1]
	v_and_b32_e32 v85, 4, v82
	v_cndmask_b32_e64 v84, 0, 1, s[0:1]
	v_cmp_eq_u32_e64 s[0:1], 0, v85
	v_cmp_gt_f32_e64 s[4:5], v75, v83
	s_and_b64 s[0:1], s[0:1], s[4:5]
	v_cndmask_b32_e64 v83, v83, v75, s[0:1]
	v_and_b32_e32 v85, 8, v82
	v_cmp_eq_u32_e64 s[4:5], 0, v85
	v_cmp_gt_f32_e64 s[8:9], v76, v83
	s_and_b64 s[4:5], s[4:5], s[8:9]
	v_cndmask_b32_e64 v83, v83, v76, s[4:5]
	v_and_b32_e32 v85, 16, v82
	v_cmp_eq_u32_e64 s[8:9], 0, v85
	v_cmp_gt_f32_e64 s[10:11], v78, v83
	s_and_b64 s[8:9], s[8:9], s[10:11]
	v_cndmask_b32_e64 v83, v83, v78, s[8:9]
	v_and_b32_e32 v85, 32, v82
	v_cmp_eq_u32_e64 s[10:11], 0, v85
	v_cmp_gt_f32_e64 s[14:15], v79, v83
	s_and_b64 s[10:11], s[10:11], s[14:15]
	v_cndmask_b32_e64 v83, v83, v79, s[10:11]
	v_and_b32_e32 v85, 64, v82
	v_cmp_eq_u32_e64 s[14:15], 0, v85
	v_cmp_gt_f32_e64 s[16:17], v80, v83
	s_and_b64 s[14:15], s[14:15], s[16:17]
	v_cndmask_b32_e64 v83, v83, v80, s[14:15]
	v_and_b32_e32 v85, 0x80, v82
	v_cmp_eq_u32_e64 s[16:17], 0, v85
	v_cmp_gt_f32_e64 s[18:19], v81, v83
	s_and_b64 s[16:17], s[16:17], s[18:19]
	v_and_b32_e32 v85, 0x100, v82
	v_cndmask_b32_e64 v83, v83, v81, s[16:17]
	v_cmp_eq_u32_e64 s[18:19], 0, v85
	s_and_b64 s[20:21], s[66:67], s[18:19]
	v_cmp_gt_f32_e64 s[18:19], v92, v83
	s_and_b64 s[18:19], s[20:21], s[18:19]
	v_and_b32_e32 v85, 0x200, v82
	v_cndmask_b32_e64 v83, v83, v92, s[18:19]
	v_cmp_eq_u32_e64 s[20:21], 0, v85
	s_and_b64 s[22:23], s[68:69], s[20:21]
	v_cmp_gt_f32_e64 s[20:21], v95, v83
	s_and_b64 s[20:21], s[22:23], s[20:21]
	v_and_b32_e32 v85, 0x400, v82
	v_cndmask_b32_e64 v83, v83, v95, s[20:21]
	v_cmp_eq_u32_e64 s[22:23], 0, v85
	s_and_b64 s[24:25], s[70:71], s[22:23]
	v_cmp_gt_f32_e64 s[22:23], v94, v83
	s_and_b64 s[22:23], s[24:25], s[22:23]
	v_and_b32_e32 v85, 0x800, v82
	v_cndmask_b32_e64 v83, v83, v94, s[22:23]
	v_cmp_eq_u32_e64 s[24:25], 0, v85
	s_and_b64 s[26:27], s[72:73], s[24:25]
	v_cmp_gt_f32_e64 s[24:25], v113, v83
	s_and_b64 s[24:25], s[26:27], s[24:25]
	v_and_b32_e32 v85, 0x1000, v82
	v_cndmask_b32_e64 v83, v83, v113, s[24:25]
	v_cmp_eq_u32_e64 s[26:27], 0, v85
	s_and_b64 s[28:29], s[74:75], s[26:27]
	v_cmp_gt_f32_e64 s[26:27], v112, v83
	s_and_b64 s[26:27], s[28:29], s[26:27]
	v_and_b32_e32 v85, 0x2000, v82
	v_cndmask_b32_e64 v83, v83, v112, s[26:27]
	v_cmp_eq_u32_e64 s[28:29], 0, v85
	s_and_b64 s[30:31], s[76:77], s[28:29]
	v_cmp_gt_f32_e64 s[28:29], v115, v83
	s_and_b64 s[28:29], s[30:31], s[28:29]
	v_and_b32_e32 v85, 0x4000, v82
	v_cndmask_b32_e64 v83, v83, v115, s[28:29]
	v_cmp_gt_f32_e64 s[34:35], v114, v83
	v_lshlrev_b32_e64 v83, v84, 1
	v_cndmask_b32_e64 v83, v83, 4, s[0:1]
	v_cndmask_b32_e64 v83, v83, 8, s[4:5]
	v_cndmask_b32_e64 v83, v83, 16, s[8:9]
	v_cndmask_b32_e64 v83, v83, 32, s[10:11]
	v_cndmask_b32_e64 v83, v83, 64, s[14:15]
	v_cndmask_b32_e64 v83, v83, v160, s[16:17]
	v_cndmask_b32_e64 v83, v83, v161, s[18:19]
	v_cndmask_b32_e64 v83, v83, v162, s[20:21]
	v_cndmask_b32_e64 v83, v83, v163, s[22:23]
	v_or_b32_e32 v85, s80, v85
	v_cndmask_b32_e64 v83, v83, v164, s[24:25]
	v_cmp_eq_u32_e64 s[30:31], 0, v85
	v_cndmask_b32_e64 v83, v83, v165, s[26:27]
	v_cndmask_b32_e64 v83, v83, v166, s[28:29]
	s_and_b64 s[0:1], s[30:31], s[34:35]
	v_cndmask_b32_e64 v83, v83, v167, s[0:1]
	v_or_b32_e32 v84, v83, v82
	v_and_b32_e32 v85, 1, v84
	v_cmp_eq_u32_e64 s[0:1], 1, v85
	s_or_b64 vcc, s[0:1], vcc
	v_cndmask_b32_e32 v11, v11, v159, vcc
	v_bitop3_b32 v85, v83, 2, v82 bitop3:0xc8
	v_cmp_eq_u32_e32 vcc, 0, v85
	v_cmp_gt_f32_e64 s[0:1], v13, v11
	s_and_b64 vcc, vcc, s[0:1]
	v_cndmask_b32_e32 v11, v11, v13, vcc
	v_bitop3_b32 v13, v83, 4, v82 bitop3:0xc8
	v_cndmask_b32_e64 v85, 0, 1, vcc
	v_cmp_eq_u32_e32 vcc, 0, v13
	v_cmp_gt_f32_e64 s[0:1], v75, v11
	s_and_b64 vcc, vcc, s[0:1]
	v_cndmask_b32_e32 v11, v11, v75, vcc
	v_bitop3_b32 v13, v83, 8, v82 bitop3:0xc8
	v_cmp_eq_u32_e64 s[0:1], 0, v13
	v_cmp_gt_f32_e64 s[4:5], v76, v11
	s_and_b64 s[0:1], s[0:1], s[4:5]
	v_cndmask_b32_e64 v11, v11, v76, s[0:1]
	v_bitop3_b32 v13, v83, 16, v82 bitop3:0xc8
	v_cmp_eq_u32_e64 s[4:5], 0, v13
	v_cmp_gt_f32_e64 s[8:9], v78, v11
	s_and_b64 s[4:5], s[4:5], s[8:9]
	v_cndmask_b32_e64 v11, v11, v78, s[4:5]
	v_bitop3_b32 v13, v83, 32, v82 bitop3:0xc8
	v_cmp_eq_u32_e64 s[8:9], 0, v13
	v_cmp_gt_f32_e64 s[10:11], v79, v11
	s_and_b64 s[8:9], s[8:9], s[10:11]
	v_cndmask_b32_e64 v11, v11, v79, s[8:9]
	v_bitop3_b32 v13, v83, 64, v82 bitop3:0xc8
	v_cmp_eq_u32_e64 s[10:11], 0, v13
	v_cmp_gt_f32_e64 s[14:15], v80, v11
	s_and_b64 s[10:11], s[10:11], s[14:15]
	s_movk_i32 s14, 0x80
	v_cndmask_b32_e64 v11, v11, v80, s[10:11]
	v_bitop3_b32 v13, v83, s14, v82 bitop3:0xc8
	v_cmp_eq_u32_e64 s[14:15], 0, v13
	v_cmp_gt_f32_e64 s[16:17], v81, v11
	s_and_b64 s[14:15], s[14:15], s[16:17]
	s_movk_i32 s16, 0x100
	v_bitop3_b32 v13, v83, s16, v82 bitop3:0xc8
	v_cndmask_b32_e64 v11, v11, v81, s[14:15]
	v_cmp_eq_u32_e64 s[16:17], 0, v13
	s_and_b64 s[18:19], s[66:67], s[16:17]
	v_cmp_gt_f32_e64 s[16:17], v92, v11
	s_and_b64 s[16:17], s[18:19], s[16:17]
	s_movk_i32 s18, 0x200
	v_bitop3_b32 v13, v83, s18, v82 bitop3:0xc8
	v_cndmask_b32_e64 v11, v11, v92, s[16:17]
	v_cmp_eq_u32_e64 s[18:19], 0, v13
	s_and_b64 s[20:21], s[68:69], s[18:19]
	v_cmp_gt_f32_e64 s[18:19], v95, v11
	s_and_b64 s[18:19], s[20:21], s[18:19]
	s_movk_i32 s20, 0x400
	v_bitop3_b32 v13, v83, s20, v82 bitop3:0xc8
	v_cndmask_b32_e64 v11, v11, v95, s[18:19]
	v_cmp_eq_u32_e64 s[20:21], 0, v13
	s_and_b64 s[22:23], s[70:71], s[20:21]
	v_cmp_gt_f32_e64 s[20:21], v94, v11
	s_and_b64 s[20:21], s[22:23], s[20:21]
	s_movk_i32 s22, 0x800
	v_bitop3_b32 v13, v83, s22, v82 bitop3:0xc8
	v_cndmask_b32_e64 v11, v11, v94, s[20:21]
	v_cmp_eq_u32_e64 s[22:23], 0, v13
	s_and_b64 s[24:25], s[72:73], s[22:23]
	v_cmp_gt_f32_e64 s[22:23], v113, v11
	s_and_b64 s[22:23], s[24:25], s[22:23]
	s_movk_i32 s24, 0x1000
	v_bitop3_b32 v13, v83, s24, v82 bitop3:0xc8
	v_cndmask_b32_e64 v11, v11, v113, s[22:23]
	v_cmp_eq_u32_e64 s[24:25], 0, v13
	s_and_b64 s[26:27], s[74:75], s[24:25]
	v_cmp_gt_f32_e64 s[24:25], v112, v11
	s_and_b64 s[24:25], s[26:27], s[24:25]
	s_movk_i32 s26, 0x2000
	v_bitop3_b32 v13, v83, s26, v82 bitop3:0xc8
	v_cndmask_b32_e64 v11, v11, v112, s[24:25]
	v_cmp_eq_u32_e64 s[26:27], 0, v13
	s_and_b64 s[28:29], s[76:77], s[26:27]
	v_cmp_gt_f32_e64 s[26:27], v115, v11
	s_and_b64 s[26:27], s[28:29], s[26:27]
	s_movk_i32 s28, 0x4000
	v_cndmask_b32_e64 v11, v11, v115, s[26:27]
	v_cmp_gt_f32_e64 s[30:31], v114, v11
	v_lshlrev_b32_e64 v11, v85, 1
	v_cndmask_b32_e64 v11, v11, 4, vcc
	v_bitop3_b32 v13, v83, s28, v82 bitop3:0xc8
	v_cndmask_b32_e64 v11, v11, 8, s[0:1]
	v_or_b32_e32 v13, s80, v13
	v_cndmask_b32_e64 v11, v11, 16, s[4:5]
	v_cndmask_b32_e64 v11, v11, 32, s[8:9]
	v_pk_mul_f32 v[0:1], v[0:1], v[12:13] op_sel_hi:[1,0]
	v_cndmask_b32_e64 v11, v11, 64, s[10:11]
	v_cvt_pk_bf16_f32 v128, v0, v1
	v_pk_mul_f32 v[0:1], v[22:23], v[12:13] op_sel_hi:[1,0]
	v_cndmask_b32_e64 v11, v11, v160, s[14:15]
	v_cvt_pk_bf16_f32 v132, v0, v1
	v_pk_mul_f32 v[0:1], v[32:33], v[12:13] op_sel_hi:[1,0]
	v_cndmask_b32_e64 v11, v11, v161, s[16:17]
	v_cvt_pk_bf16_f32 v136, v0, v1
	v_mov_b32_e32 v0, v31
	v_mov_b32_e32 v1, v65
	v_cndmask_b32_e64 v11, v11, v162, s[18:19]
	v_pk_mul_f32 v[2:3], v[2:3], v[12:13] op_sel_hi:[1,0]
	v_pk_mul_f32 v[0:1], v[0:1], v[12:13] op_sel_hi:[1,0]
	v_cndmask_b32_e64 v11, v11, v163, s[20:21]
	v_pk_mul_f32 v[14:15], v[14:15], v[12:13] op_sel_hi:[1,0]
	v_cvt_pk_bf16_f32 v130, v2, v3
	v_pk_mul_f32 v[2:3], v[42:43], v[12:13] op_sel_hi:[1,0]
	v_cvt_pk_bf16_f32 v140, v0, v1
	v_add_u32_e32 v0, 0x2000, v6
	v_cndmask_b32_e64 v11, v11, v164, s[22:23]
	v_cvt_pk_bf16_f32 v129, v14, v15
	v_pk_mul_f32 v[14:15], v[28:29], v[12:13] op_sel_hi:[1,0]
	v_cvt_pk_bf16_f32 v133, v2, v3
	v_mov_b32_e32 v2, v37
	v_mov_b32_e32 v3, v59
	v_lshrrev_b32_e32 v0, 8, v0
	v_cmp_eq_u32_e64 s[28:29], 0, v13
	v_cndmask_b32_e64 v11, v11, v165, s[24:25]
	v_pk_mul_f32 v[16:17], v[16:17], v[12:13] op_sel_hi:[1,0]
	v_cvt_pk_bf16_f32 v134, v14, v15
	v_pk_mul_f32 v[2:3], v[2:3], v[12:13] op_sel_hi:[1,0]
	v_pk_mul_f32 v[14:15], v[34:35], v[12:13] op_sel_hi:[1,0]
	v_mov_b32_e32 v31, v64
	v_lshrrev_b32_e32 v1, 4, v4
	v_mul_i32_i24_e32 v180, 0x110, v0
	v_and_b32_e32 v0, 7, v4
	v_cndmask_b32_e64 v11, v11, v166, s[26:27]
	s_and_b64 vcc, s[28:29], s[30:31]
	v_cvt_pk_bf16_f32 v131, v16, v17
	v_pk_mul_f32 v[16:17], v[48:49], v[12:13] op_sel_hi:[1,0]
	v_mov_b32_e32 v37, v58
	v_cvt_pk_bf16_f32 v137, v2, v3
	v_cvt_pk_bf16_f32 v138, v14, v15
	v_mov_b32_e32 v2, v71
	v_mov_b32_e32 v3, v73
	v_pk_mul_f32 v[14:15], v[30:31], v[12:13] op_sel_hi:[1,0]
	v_mov_b32_e32 v71, v72
	v_mul_lo_u32 v179, v1, s52
	v_lshlrev_b32_e32 v0, 4, v0
	v_mov_b32_e32 v1, v145
	v_cndmask_b32_e32 v11, v11, v167, vcc
	v_pk_mul_f32 v[60:61], v[60:61], v[12:13] op_sel_hi:[1,0]
	v_pk_mul_f32 v[66:67], v[66:67], v[12:13] op_sel_hi:[1,0]
	v_pk_mul_f32 v[62:63], v[62:63], v[12:13] op_sel_hi:[1,0]
	v_pk_mul_f32 v[68:69], v[68:69], v[12:13] op_sel_hi:[1,0]
	v_pk_mul_f32 v[50:51], v[50:51], v[12:13] op_sel_hi:[1,0]
	v_pk_mul_f32 v[54:55], v[54:55], v[12:13] op_sel_hi:[1,0]
	v_pk_mul_f32 v[52:53], v[52:53], v[12:13] op_sel_hi:[1,0]
	v_pk_mul_f32 v[56:57], v[56:57], v[12:13] op_sel_hi:[1,0]
	v_pk_mul_f32 v[38:39], v[38:39], v[12:13] op_sel_hi:[1,0]
	v_pk_mul_f32 v[44:45], v[44:45], v[12:13] op_sel_hi:[1,0]
	v_pk_mul_f32 v[40:41], v[40:41], v[12:13] op_sel_hi:[1,0]
	v_pk_mul_f32 v[46:47], v[46:47], v[12:13] op_sel_hi:[1,0]
	v_pk_mul_f32 v[18:19], v[18:19], v[12:13] op_sel_hi:[1,0]
	v_pk_mul_f32 v[24:25], v[24:25], v[12:13] op_sel_hi:[1,0]
	v_pk_mul_f32 v[20:21], v[20:21], v[12:13] op_sel_hi:[1,0]
	v_pk_mul_f32 v[26:27], v[26:27], v[12:13] op_sel_hi:[1,0]
	v_cvt_pk_bf16_f32 v135, v16, v17
	v_pk_mul_f32 v[16:17], v[36:37], v[12:13] op_sel_hi:[1,0]
	v_pk_mul_f32 v[2:3], v[2:3], v[12:13] op_sel_hi:[1,0]
	v_pk_mul_f32 v[12:13], v[70:71], v[12:13] op_sel_hi:[1,0]
	v_cvt_pk_bf16_f32 v142, v14, v15
	v_lshl_add_u64 v[0:1], v[8:9], 0, v[0:1]
	v_mov_b32_e32 v14, v145
	v_mov_b32_e32 v15, v145
	v_or_b32_e32 v173, v11, v84
	v_cvt_pk_bf16_f32 v112, v60, v61
	v_cvt_pk_bf16_f32 v114, v62, v63
	v_cvt_pk_bf16_f32 v116, v50, v51
	v_cvt_pk_bf16_f32 v117, v54, v55
	v_cvt_pk_bf16_f32 v118, v52, v53
	v_cvt_pk_bf16_f32 v119, v56, v57
	v_cvt_pk_bf16_f32 v120, v38, v39
	v_cvt_pk_bf16_f32 v121, v44, v45
	v_cvt_pk_bf16_f32 v122, v40, v41
	v_cvt_pk_bf16_f32 v123, v46, v47
	v_cvt_pk_bf16_f32 v124, v18, v19
	v_cvt_pk_bf16_f32 v125, v24, v25
	v_cvt_pk_bf16_f32 v126, v20, v21
	v_cvt_pk_bf16_f32 v127, v26, v27
	v_cvt_pk_bf16_f32 v139, v16, v17
	v_cvt_pk_bf16_f32 v141, v2, v3
	v_cvt_pk_bf16_f32 v143, v12, v13
	v_lshl_add_u64 v[150:151], s[88:89], 0, v[0:1]
	v_mov_b32_e32 v0, v145
	v_mov_b32_e32 v1, v145
	v_mov_b32_e32 v2, v145
	v_mov_b32_e32 v3, v145
	v_mov_b32_e32 v4, v145
	v_mov_b32_e32 v6, v145
	v_mov_b32_e32 v8, v145
	v_mov_b32_e32 v9, v145
	v_mov_b32_e32 v11, v145
	v_mov_b32_e32 v12, v145
	v_mov_b32_e32 v13, v145
	v_mov_b64_e32 v[30:31], v[14:15]
	v_mov_b64_e32 v[46:47], v[14:15]
	v_mov_b64_e32 v[62:63], v[14:15]
	v_cvt_pk_bf16_f32 v113, v66, v67
	v_cvt_pk_bf16_f32 v115, v68, v69
	s_or_b32 s14, s79, 3
	v_mov_b64_e32 v[28:29], v[12:13]
	v_mov_b64_e32 v[26:27], v[10:11]
	v_mov_b64_e32 v[24:25], v[8:9]
	v_mov_b64_e32 v[22:23], v[6:7]
	v_mov_b64_e32 v[20:21], v[4:5]
	v_mov_b64_e32 v[18:19], v[2:3]
	v_mov_b64_e32 v[16:17], v[0:1]
	v_mov_b64_e32 v[44:45], v[12:13]
	v_mov_b64_e32 v[42:43], v[10:11]
	v_mov_b64_e32 v[40:41], v[8:9]
	v_mov_b64_e32 v[38:39], v[6:7]
	v_mov_b64_e32 v[36:37], v[4:5]
	v_mov_b64_e32 v[34:35], v[2:3]
	v_mov_b64_e32 v[32:33], v[0:1]
	v_mov_b64_e32 v[60:61], v[12:13]
	v_mov_b64_e32 v[58:59], v[10:11]
	v_mov_b64_e32 v[56:57], v[8:9]
	v_mov_b64_e32 v[54:55], v[6:7]
	v_mov_b64_e32 v[52:53], v[4:5]
	v_mov_b64_e32 v[50:51], v[2:3]
	v_mov_b64_e32 v[48:49], v[0:1]
	s_movk_i32 s26, 0xffe0
	s_branch .LBB0_1729

.LBB0_1728:
	s_or_b64 exec, exec, s[4:5]
	s_add_u32 s98, s98, 0x4000
	s_addc_u32 s99, s99, 0
	s_add_u32 s100, s100, 0x4000
	s_addc_u32 s101, s101, 0
	s_add_u32 s44, s44, 0x80
	s_addc_u32 s45, s45, 0
	s_add_u32 s46, s46, 0x80
	s_addc_u32 s47, s47, 0
	s_add_i32 s84, s84, 1
	s_cmp_eq_u32 s14, s84
	s_cbranch_scc1 .LBB0_1740
.LBB0_1729:
	s_and_b32 s0, s84, 1
	s_mul_i32 s1, s0, 0x4400
	s_add_i32 s16, s1, 0
	v_add3_u32 v64, s16, v179, v177
	s_lshl_b32 s0, s0, 10
	s_waitcnt vmcnt(3)
	ds_write_b128 v64, v[100:103]
	v_add3_u32 v64, s16, v180, v177
	s_add_i32 s15, s16, s0
	s_waitcnt vmcnt(2)
	ds_write_b128 v64, v[96:99]
	v_add3_u32 v64, s15, v176, v178
	s_waitcnt vmcnt(1)
	ds_write_b128 v64, v[104:107] offset:34816
	s_waitcnt vmcnt(0)
	ds_write_b128 v64, v[108:111] offset:44032
	v_lshl_add_u64 v[66:67], v[152:153], 0, s[98:99]
	v_lshl_add_u64 v[64:65], v[152:153], 0, s[100:101]
	s_waitcnt lgkmcnt(0)
	s_barrier
	global_load_dwordx4 v[100:103], v[66:67], off
	global_load_dwordx4 v[96:99], v[64:65], off
	v_lshl_add_u64 v[66:67], v[150:151], 0, s[44:45]
	s_lshr_b32 s0, s84, 2
	v_lshl_add_u64 v[64:65], v[150:151], 0, s[46:47]
	s_cmp_eq_u32 s0, s81
	global_load_dwordx4 v[104:107], v[66:67], off offset:128
	global_load_dwordx4 v[108:111], v[64:65], off offset:128
	s_cselect_b64 s[8:9], -1, 0
	s_lshl_b32 s1, 1, s0
	v_and_b32_e32 v64, s1, v173
	s_cmp_lg_u32 s0, s81
	v_cmp_ne_u32_e64 s[0:1], 0, v64
	s_mov_b64 s[4:5], -1
	s_cbranch_scc0 .LBB0_1732
	v_cndmask_b32_e64 v64, 0, 1, s[0:1]
	v_cmp_ne_u32_e32 vcc, 0, v64
	s_cmp_lg_u64 vcc, 0
	s_cselect_b64 s[10:11], -1, 0
	s_and_b32 s17, s84, 3
	s_cbranch_execz .LBB0_1733

.LBB0_1769:
	s_waitcnt lgkmcnt(0)
	v_add_f32_e32 v7, v7, v75
	v_fmamk_f32 v7, v7, 0x3c000000, v158
	v_lshlrev_b64 v[148:149], 11, v[8:9]
	v_mul_f32_e32 v8, 0x4b800000, v7
	v_cmp_gt_f32_e32 vcc, s92, v7
	v_and_b32_e32 v76, 31, v0
	v_lshlrev_b32_e32 v147, 2, v1
	v_cndmask_b32_e32 v7, v7, v8, vcc
	v_rsq_f32_e32 v7, v7
	v_mov_b32_e32 v1, v145
	s_and_b32 s0, s2, 7
	s_lshl_b32 s0, s0, 2
	v_mul_f32_e32 v8, 0x45800000, v7
	v_cndmask_b32_e32 v7, v7, v8, vcc
	v_mul_f32_e32 v8, 0x3e0293ee, v7
	v_pk_mul_f32 v[14:15], v[14:15], v[8:9] op_sel_hi:[1,0]
	v_pk_mul_f32 v[16:17], v[16:17], v[8:9] op_sel_hi:[1,0]
	v_cvt_pk_bf16_f32 v114, v14, v15
	v_pk_mul_f32 v[12:13], v[12:13], v[8:9] op_sel_hi:[1,0]
	v_pk_mul_f32 v[14:15], v[24:25], v[8:9] op_sel_hi:[1,0]
	v_pk_mul_f32 v[10:11], v[10:11], v[8:9] op_sel_hi:[1,0]
	v_cvt_pk_bf16_f32 v112, v16, v17
	v_pk_mul_f32 v[16:17], v[22:23], v[8:9] op_sel_hi:[1,0]
	v_cvt_pk_bf16_f32 v116, v12, v13
	v_cvt_pk_bf16_f32 v117, v14, v15
	v_cvt_pk_bf16_f32 v118, v10, v11
	v_pk_mul_f32 v[10:11], v[26:27], v[8:9] op_sel_hi:[1,0]
	v_pk_mul_f32 v[12:13], v[32:33], v[8:9] op_sel_hi:[1,0]
	v_pk_mul_f32 v[14:15], v[28:29], v[8:9] op_sel_hi:[1,0]
	v_cvt_pk_bf16_f32 v119, v16, v17
	v_pk_mul_f32 v[16:17], v[30:31], v[8:9] op_sel_hi:[1,0]
	v_cvt_pk_bf16_f32 v120, v10, v11
	v_cvt_pk_bf16_f32 v121, v12, v13
	v_cvt_pk_bf16_f32 v122, v14, v15
	v_pk_mul_f32 v[10:11], v[36:37], v[8:9] op_sel_hi:[1,0]
	v_pk_mul_f32 v[12:13], v[40:41], v[8:9] op_sel_hi:[1,0]
	v_pk_mul_f32 v[14:15], v[34:35], v[8:9] op_sel_hi:[1,0]
	v_cvt_pk_bf16_f32 v123, v16, v17
	v_pk_mul_f32 v[16:17], v[38:39], v[8:9] op_sel_hi:[1,0]
	v_cvt_pk_bf16_f32 v124, v10, v11
	v_cvt_pk_bf16_f32 v125, v12, v13
	v_cvt_pk_bf16_f32 v126, v14, v15
	v_pk_mul_f32 v[10:11], v[44:45], v[8:9] op_sel_hi:[1,0]
	v_pk_mul_f32 v[12:13], v[48:49], v[8:9] op_sel_hi:[1,0]
	v_pk_mul_f32 v[14:15], v[42:43], v[8:9] op_sel_hi:[1,0]
	v_cvt_pk_bf16_f32 v127, v16, v17
	v_pk_mul_f32 v[16:17], v[46:47], v[8:9] op_sel_hi:[1,0]
	v_cvt_pk_bf16_f32 v128, v10, v11
	v_cvt_pk_bf16_f32 v129, v12, v13
	v_cvt_pk_bf16_f32 v130, v14, v15
	v_pk_mul_f32 v[10:11], v[52:53], v[8:9] op_sel_hi:[1,0]
	v_pk_mul_f32 v[12:13], v[56:57], v[8:9] op_sel_hi:[1,0]
	v_pk_mul_f32 v[14:15], v[50:51], v[8:9] op_sel_hi:[1,0]
	v_cvt_pk_bf16_f32 v131, v16, v17
	v_pk_mul_f32 v[16:17], v[54:55], v[8:9] op_sel_hi:[1,0]
	v_cvt_pk_bf16_f32 v132, v10, v11
	v_cvt_pk_bf16_f32 v133, v12, v13
	v_cvt_pk_bf16_f32 v134, v14, v15
	v_pk_mul_f32 v[10:11], v[60:61], v[8:9] op_sel_hi:[1,0]
	v_pk_mul_f32 v[12:13], v[64:65], v[8:9] op_sel_hi:[1,0]
	v_pk_mul_f32 v[14:15], v[58:59], v[8:9] op_sel_hi:[1,0]
	v_pk_mul_f32 v[20:21], v[20:21], v[8:9] op_sel_hi:[1,0]
	v_pk_mul_f32 v[18:19], v[18:19], v[8:9] op_sel_hi:[1,0]
	v_cvt_pk_bf16_f32 v135, v16, v17
	v_pk_mul_f32 v[16:17], v[62:63], v[8:9] op_sel_hi:[1,0]
	v_cvt_pk_bf16_f32 v136, v10, v11
	v_cvt_pk_bf16_f32 v137, v12, v13
	v_cvt_pk_bf16_f32 v138, v14, v15
	v_pk_mul_f32 v[10:11], v[68:69], v[8:9] op_sel_hi:[1,0]
	v_pk_mul_f32 v[12:13], v[70:71], v[8:9] op_sel_hi:[1,0]
	v_pk_mul_f32 v[14:15], v[66:67], v[8:9] op_sel_hi:[1,0]
	v_pk_mul_f32 v[8:9], v[72:73], v[8:9] op_sel_hi:[1,0]
	v_add_u32_e32 v7, 0x2000, v2
	v_cvt_pk_bf16_f32 v143, v8, v9
	v_lshrrev_b32_e32 v8, 4, v0
	v_and_b32_e32 v0, 7, v0
	v_lshlrev_b32_e32 v0, 4, v0
	v_cvt_pk_bf16_f32 v142, v14, v15
	v_lshrrev_b32_e32 v7, 8, v7
	v_lshl_add_u64 v[0:1], v[4:5], 0, v[0:1]
	v_mov_b32_e32 v14, v145
	v_mov_b32_e32 v15, v145
	v_cvt_pk_bf16_f32 v113, v20, v21
	v_cvt_pk_bf16_f32 v115, v18, v19
	v_cvt_pk_bf16_f32 v139, v16, v17
	v_cvt_pk_bf16_f32 v140, v10, v11
	v_cvt_pk_bf16_f32 v141, v12, v13
	v_mul_lo_u32 v179, v8, s52
	v_and_b32_e32 v177, 0xf0, v2
	v_mul_i32_i24_e32 v180, 0x110, v7
	v_mul_lo_u32 v176, v6, s97
	v_and_b32_e32 v178, 0x70, v2
	v_lshl_add_u64 v[150:151], s[88:89], 0, v[0:1]
	v_lshl_add_u64 v[152:153], s[88:89], 0, v[2:3]
	v_mov_b32_e32 v0, v145
	v_mov_b32_e32 v1, v145
	v_mov_b32_e32 v2, v145
	v_mov_b32_e32 v3, v145
	v_mov_b32_e32 v4, v145
	v_mov_b32_e32 v5, v145
	v_mov_b32_e32 v6, v145
	v_mov_b32_e32 v7, v145
	v_mov_b32_e32 v8, v145
	v_mov_b32_e32 v9, v145
	v_mov_b32_e32 v10, v145
	v_mov_b32_e32 v11, v145
	v_mov_b32_e32 v12, v145
	v_mov_b32_e32 v13, v145
	v_mov_b64_e32 v[30:31], v[14:15]
	v_mov_b64_e32 v[46:47], v[14:15]
	v_mov_b64_e32 v[62:63], v[14:15]
	v_and_b32_e32 v173, 0xffffffe0, v74
	s_or_b32 s14, s0, 3
	v_or_b32_e32 v175, 31, v74
	v_mul_u32_u24_e32 v174, 0x110, v76
	v_mul_u32_u24_e32 v171, 0x90, v76
	s_mov_b32 s15, 0
	s_add_u32 s98, s12, s6
	s_addc_u32 s99, s13, 0
	s_add_u32 s100, s12, s7
	s_addc_u32 s101, s13, 0
	s_add_u32 s44, s12, s59
	s_addc_u32 s45, s13, 0
	s_add_u32 s46, s12, 0x31e80000
	s_addc_u32 s47, s13, 0
	v_mov_b32_e32 v154, 0xf149f2ca
	v_mov_b32_e32 v170, 0
	v_mov_b64_e32 v[28:29], v[12:13]
	v_mov_b64_e32 v[26:27], v[10:11]
	v_mov_b64_e32 v[24:25], v[8:9]
	v_mov_b64_e32 v[22:23], v[6:7]
	v_mov_b64_e32 v[20:21], v[4:5]
	v_mov_b64_e32 v[18:19], v[2:3]
	v_mov_b64_e32 v[16:17], v[0:1]
	v_mov_b64_e32 v[44:45], v[12:13]
	v_mov_b64_e32 v[42:43], v[10:11]
	v_mov_b64_e32 v[40:41], v[8:9]
	v_mov_b64_e32 v[38:39], v[6:7]
	v_mov_b64_e32 v[36:37], v[4:5]
	v_mov_b64_e32 v[34:35], v[2:3]
	v_mov_b64_e32 v[32:33], v[0:1]
	v_mov_b64_e32 v[60:61], v[12:13]
	v_mov_b64_e32 v[58:59], v[10:11]
	v_mov_b64_e32 v[56:57], v[8:9]
	v_mov_b64_e32 v[54:55], v[6:7]
	v_mov_b64_e32 v[52:53], v[4:5]
	v_mov_b64_e32 v[50:51], v[2:3]
	v_mov_b64_e32 v[48:49], v[0:1]
	s_branch .LBB0_1772

.LBB0_1771:
	s_or_b64 exec, exec, s[4:5]
	s_add_u32 s98, s98, 0x4000
	s_addc_u32 s99, s99, 0
	s_add_u32 s100, s100, 0x4000
	s_addc_u32 s101, s101, 0
	s_add_u32 s44, s44, 0x80
	s_addc_u32 s45, s45, 0
	s_add_u32 s46, s46, 0x80
	s_addc_u32 s47, s47, 0
	s_add_i32 s15, s15, 1
	s_cmp_eq_u32 s14, s15
	s_cbranch_scc1 .LBB0_1783
.LBB0_1772:
	s_and_b32 s0, s15, 1
	s_mul_i32 s1, s0, 0x4400
	s_add_i32 s17, s1, 0
	v_add3_u32 v64, s17, v179, v177
	s_lshl_b32 s0, s0, 10
	s_waitcnt vmcnt(3)
	ds_write_b128 v64, v[100:103]
	v_add3_u32 v64, s17, v180, v177
	s_add_i32 s16, s17, s0
	s_waitcnt vmcnt(2)
	ds_write_b128 v64, v[96:99]
	v_add3_u32 v64, s16, v176, v178
	s_waitcnt vmcnt(1)
	ds_write_b128 v64, v[104:107] offset:34816
	s_waitcnt vmcnt(0)
	ds_write_b128 v64, v[108:111] offset:44032
	v_lshl_add_u64 v[66:67], v[152:153], 0, s[98:99]
	v_lshl_add_u64 v[64:65], v[152:153], 0, s[100:101]
	s_waitcnt lgkmcnt(0)
	s_barrier
	global_load_dwordx4 v[100:103], v[66:67], off
	global_load_dwordx4 v[96:99], v[64:65], off
	v_lshl_add_u64 v[66:67], v[150:151], 0, s[44:45]
	s_lshr_b32 s0, s15, 2
	v_lshl_add_u64 v[64:65], v[150:151], 0, s[46:47]
	s_cmp_eq_u32 s0, s80
	global_load_dwordx4 v[104:107], v[66:67], off offset:128
	global_load_dwordx4 v[108:111], v[64:65], off offset:128
	s_cselect_b64 s[8:9], -1, 0
	s_lshl_b32 s1, 1, s0
	v_and_b32_e32 v64, s1, v172
	s_cmp_lg_u32 s0, s80
	v_cmp_ne_u32_e64 s[0:1], 0, v64
	s_mov_b64 s[4:5], -1
	s_cbranch_scc0 .LBB0_1775
	v_cndmask_b32_e64 v64, 0, 1, s[0:1]
	v_cmp_ne_u32_e32 vcc, 0, v64
	s_cmp_lg_u64 vcc, 0
	s_cselect_b64 s[10:11], -1, 0
	s_and_b32 s18, s15, 3
	s_cbranch_execz .LBB0_1776

	.amdhsa_kernel _Z4mega4Args
		.amdhsa_group_segment_fixed_size 0
		.amdhsa_private_segment_fixed_size 0
		.amdhsa_kernarg_size 408
		.amdhsa_user_sgpr_count 2
		.amdhsa_user_sgpr_dispatch_ptr 0
		.amdhsa_user_sgpr_queue_ptr 0
		.amdhsa_user_sgpr_kernarg_segment_ptr 1
		.amdhsa_user_sgpr_dispatch_id 0
		.amdhsa_user_sgpr_kernarg_preload_length 0
		.amdhsa_user_sgpr_kernarg_preload_offset 0
		.amdhsa_user_sgpr_private_segment_size 0
		.amdhsa_uses_dynamic_stack 0
		.amdhsa_enable_private_segment 0
		.amdhsa_system_sgpr_workgroup_id_x 1
		.amdhsa_system_sgpr_workgroup_id_y 0
		.amdhsa_system_sgpr_workgroup_id_z 0
		.amdhsa_system_sgpr_workgroup_info 0
		.amdhsa_system_vgpr_workitem_id 2
		.amdhsa_next_free_vgpr 248
		.amdhsa_next_free_sgpr 102
		.amdhsa_accum_offset 248
		.amdhsa_reserve_vcc 1
		.amdhsa_float_round_mode_32 0
		.amdhsa_float_round_mode_16_64 0
		.amdhsa_float_denorm_mode_32 3
		.amdhsa_float_denorm_mode_16_64 3
		.amdhsa_dx10_clamp 1
		.amdhsa_ieee_mode 1
		.amdhsa_fp16_overflow 0
		.amdhsa_tg_split 0
		.amdhsa_exception_fp_ieee_invalid_op 0
		.amdhsa_exception_fp_denorm_src 0
		.amdhsa_exception_fp_ieee_div_zero 0
		.amdhsa_exception_fp_ieee_overflow 0
		.amdhsa_exception_fp_ieee_underflow 0
		.amdhsa_exception_fp_ieee_inexact 0
		.amdhsa_exception_int_div_zero 0
	.end_amdhsa_kernel

amdhsa.kernels:
  - .agpr_count:     0
    .args:
      - .offset:         0
        .size:           152
        .value_kind:     by_value
      - .offset:         152
        .size:           4
        .value_kind:     hidden_block_count_x
      - .offset:         156
        .size:           4
        .value_kind:     hidden_block_count_y
      - .offset:         160
        .size:           4
        .value_kind:     hidden_block_count_z
      - .offset:         164
        .size:           2
        .value_kind:     hidden_group_size_x
      - .offset:         166
        .size:           2
        .value_kind:     hidden_group_size_y
      - .offset:         168
        .size:           2
        .value_kind:     hidden_group_size_z
      - .offset:         170
        .size:           2
        .value_kind:     hidden_remainder_x
      - .offset:         172
        .size:           2
        .value_kind:     hidden_remainder_y
      - .offset:         174
        .size:           2
        .value_kind:     hidden_remainder_z
      - .offset:         192
        .size:           8
        .value_kind:     hidden_global_offset_x
      - .offset:         200
        .size:           8
        .value_kind:     hidden_global_offset_y
      - .offset:         208
        .size:           8
        .value_kind:     hidden_global_offset_z
      - .offset:         216
        .size:           2
        .value_kind:     hidden_grid_dims
      - .offset:         240
        .size:           8
        .value_kind:     hidden_multigrid_sync_arg
      - .offset:         272
        .size:           4
        .value_kind:     hidden_dynamic_lds_size
    .group_segment_fixed_size: 0
    .kernarg_segment_align: 8
    .kernarg_segment_size: 408
    .language:       OpenCL C
    .language_version:
      - 2
      - 0
    .max_flat_workgroup_size: 512
    .name:           _Z4mega4Args
    .private_segment_fixed_size: 0
    .sgpr_count:     108
    .sgpr_spill_count: 39
    .symbol:         _Z4mega4Args.kd
    .uniform_work_group_size: 1
    .uses_dynamic_stack: false
    .vgpr_count:     248
    .vgpr_spill_count: 0
    .wavefront_size: 64
